# chunkwise DeltaNet on f32 matrix cores, full LDS waits before every compute segment - second sitting
# speedup vs baseline: 1.0049x; 1.0039x over previous
.Ldc_b2:
	s_waitcnt lgkmcnt(0)
	s_barrier
	s_cmp_ge_u32 s60, 2
	s_cbranch_scc1 .Ldc_s2q
	s_cmp_eq_u32 s60, 1
	s_cbranch_scc1 .Ldc_s2k
	v_and_b32_e32 v135, 31, v221
	v_lshlrev_b32_e32 v135, 2, v135
	ds_read_b32 v10, v135 offset:57856
	ds_read_b32 v11, v135 offset:58000
	ds_read_b32 v12, v135 offset:58144
	ds_read_b32 v13, v135 offset:58288
	ds_read_b32 v14, v135 offset:58432
	ds_read_b32 v15, v135 offset:58576
	ds_read_b32 v16, v135 offset:58720
	ds_read_b32 v17, v135 offset:58864
	ds_read_b32 v18, v135 offset:59008
	ds_read_b32 v19, v135 offset:59152
	ds_read_b32 v20, v135 offset:59296
	ds_read_b32 v21, v135 offset:59440
	ds_read_b32 v22, v135 offset:59584
	ds_read_b32 v23, v135 offset:59728
	ds_read_b32 v24, v135 offset:59872
	ds_read_b32 v25, v135 offset:60016
	ds_read_b32 v26, v135 offset:60160
	ds_read_b32 v27, v135 offset:60304
	ds_read_b32 v28, v135 offset:60448
	ds_read_b32 v29, v135 offset:60592
	ds_read_b32 v30, v135 offset:60736
	ds_read_b32 v31, v135 offset:60880
	ds_read_b32 v32, v135 offset:61024
	ds_read_b32 v33, v135 offset:61168
	ds_read_b32 v34, v135 offset:61312
	ds_read_b32 v35, v135 offset:61456
	ds_read_b32 v36, v135 offset:61600
	ds_read_b32 v37, v135 offset:61744
	ds_read_b32 v38, v135 offset:61888
	ds_read_b32 v39, v135 offset:62032
	ds_read_b32 v40, v135 offset:62176
	ds_read_b32 v41, v135 offset:62320
	ds_read_b128 v[42:45], v1 offset:44032
	ds_read_b128 v[46:49], v1 offset:44048
	ds_read_b128 v[50:53], v1 offset:44064
	ds_read_b128 v[54:57], v1 offset:44080
	ds_read_b128 v[58:61], v1 offset:44096
	ds_read_b128 v[62:65], v1 offset:44112
	ds_read_b128 v[66:69], v1 offset:44128
	ds_read_b128 v[70:73], v1 offset:44144
	ds_read_b128 v[74:77], v1 offset:44176
	ds_read_b128 v[78:81], v1 offset:44192
	ds_read_b128 v[82:85], v1 offset:44208
	ds_read_b128 v[86:89], v1 offset:44224
	ds_read_b128 v[226:229], v1 offset:44240
	ds_read_b128 v[230:233], v1 offset:44256
	ds_read_b128 v[234:237], v1 offset:44272
	ds_read_b128 v[238:241], v1 offset:44288
	s_waitcnt lgkmcnt(0)
	v_fmac_f32_e32 v11, v43, v10
	v_pk_fma_f32 v[12:13], v[44:45], v[10:11], v[12:13] op_sel:[0,0,0] op_sel_hi:[1,0,1]
	v_pk_fma_f32 v[14:15], v[46:47], v[10:11], v[14:15] op_sel:[0,0,0] op_sel_hi:[1,0,1]
	v_pk_fma_f32 v[16:17], v[48:49], v[10:11], v[16:17] op_sel:[0,0,0] op_sel_hi:[1,0,1]
	v_pk_fma_f32 v[18:19], v[50:51], v[10:11], v[18:19] op_sel:[0,0,0] op_sel_hi:[1,0,1]
	v_pk_fma_f32 v[20:21], v[52:53], v[10:11], v[20:21] op_sel:[0,0,0] op_sel_hi:[1,0,1]
	v_pk_fma_f32 v[22:23], v[54:55], v[10:11], v[22:23] op_sel:[0,0,0] op_sel_hi:[1,0,1]
	v_pk_fma_f32 v[24:25], v[56:57], v[10:11], v[24:25] op_sel:[0,0,0] op_sel_hi:[1,0,1]
	v_pk_fma_f32 v[26:27], v[58:59], v[10:11], v[26:27] op_sel:[0,0,0] op_sel_hi:[1,0,1]
	v_pk_fma_f32 v[28:29], v[60:61], v[10:11], v[28:29] op_sel:[0,0,0] op_sel_hi:[1,0,1]
	v_pk_fma_f32 v[30:31], v[62:63], v[10:11], v[30:31] op_sel:[0,0,0] op_sel_hi:[1,0,1]
	v_pk_fma_f32 v[32:33], v[64:65], v[10:11], v[32:33] op_sel:[0,0,0] op_sel_hi:[1,0,1]
	v_pk_fma_f32 v[34:35], v[66:67], v[10:11], v[34:35] op_sel:[0,0,0] op_sel_hi:[1,0,1]
	v_pk_fma_f32 v[36:37], v[68:69], v[10:11], v[36:37] op_sel:[0,0,0] op_sel_hi:[1,0,1]
	v_pk_fma_f32 v[38:39], v[70:71], v[10:11], v[38:39] op_sel:[0,0,0] op_sel_hi:[1,0,1]
	v_pk_fma_f32 v[40:41], v[72:73], v[10:11], v[40:41] op_sel:[0,0,0] op_sel_hi:[1,0,1]
	ds_read_b128 v[42:45], v1 offset:44320
	ds_read_b128 v[46:49], v1 offset:44336
	ds_read_b128 v[50:53], v1 offset:44352
	ds_read_b128 v[54:57], v1 offset:44368
	ds_read_b128 v[58:61], v1 offset:44384
	ds_read_b128 v[62:65], v1 offset:44400
	ds_read_b128 v[66:69], v1 offset:44416
	ds_read_b128 v[70:73], v1 offset:44432
	s_waitcnt lgkmcnt(0)
	v_pk_fma_f32 v[12:13], v[76:77], v[10:11], v[12:13] op_sel:[0,1,0] op_sel_hi:[1,1,1]
	v_pk_fma_f32 v[14:15], v[78:79], v[10:11], v[14:15] op_sel:[0,1,0] op_sel_hi:[1,1,1]
	v_pk_fma_f32 v[16:17], v[80:81], v[10:11], v[16:17] op_sel:[0,1,0] op_sel_hi:[1,1,1]
	v_pk_fma_f32 v[18:19], v[82:83], v[10:11], v[18:19] op_sel:[0,1,0] op_sel_hi:[1,1,1]
	v_pk_fma_f32 v[20:21], v[84:85], v[10:11], v[20:21] op_sel:[0,1,0] op_sel_hi:[1,1,1]
	v_pk_fma_f32 v[22:23], v[86:87], v[10:11], v[22:23] op_sel:[0,1,0] op_sel_hi:[1,1,1]
	v_pk_fma_f32 v[24:25], v[88:89], v[10:11], v[24:25] op_sel:[0,1,0] op_sel_hi:[1,1,1]
	v_pk_fma_f32 v[26:27], v[226:227], v[10:11], v[26:27] op_sel:[0,1,0] op_sel_hi:[1,1,1]
	v_pk_fma_f32 v[28:29], v[228:229], v[10:11], v[28:29] op_sel:[0,1,0] op_sel_hi:[1,1,1]
	v_pk_fma_f32 v[30:31], v[230:231], v[10:11], v[30:31] op_sel:[0,1,0] op_sel_hi:[1,1,1]
	v_pk_fma_f32 v[32:33], v[232:233], v[10:11], v[32:33] op_sel:[0,1,0] op_sel_hi:[1,1,1]
	v_pk_fma_f32 v[34:35], v[234:235], v[10:11], v[34:35] op_sel:[0,1,0] op_sel_hi:[1,1,1]
	v_pk_fma_f32 v[36:37], v[236:237], v[10:11], v[36:37] op_sel:[0,1,0] op_sel_hi:[1,1,1]
	v_pk_fma_f32 v[38:39], v[238:239], v[10:11], v[38:39] op_sel:[0,1,0] op_sel_hi:[1,1,1]
	v_pk_fma_f32 v[40:41], v[240:241], v[10:11], v[40:41] op_sel:[0,1,0] op_sel_hi:[1,1,1]
	ds_read_b128 v[78:81], v1 offset:44480
	ds_read_b128 v[82:85], v1 offset:44496
	ds_read_b128 v[86:89], v1 offset:44512
	ds_read_b128 v[226:229], v1 offset:44528
	ds_read_b128 v[230:233], v1 offset:44544
	ds_read_b128 v[234:237], v1 offset:44560
	ds_read_b128 v[238:241], v1 offset:44576
	s_waitcnt lgkmcnt(0)
	v_fmac_f32_e32 v13, v45, v12
	v_pk_fma_f32 v[14:15], v[46:47], v[12:13], v[14:15] op_sel:[0,0,0] op_sel_hi:[1,0,1]
	v_pk_fma_f32 v[16:17], v[48:49], v[12:13], v[16:17] op_sel:[0,0,0] op_sel_hi:[1,0,1]
	v_pk_fma_f32 v[18:19], v[50:51], v[12:13], v[18:19] op_sel:[0,0,0] op_sel_hi:[1,0,1]
	v_pk_fma_f32 v[20:21], v[52:53], v[12:13], v[20:21] op_sel:[0,0,0] op_sel_hi:[1,0,1]
	v_pk_fma_f32 v[22:23], v[54:55], v[12:13], v[22:23] op_sel:[0,0,0] op_sel_hi:[1,0,1]
	v_pk_fma_f32 v[24:25], v[56:57], v[12:13], v[24:25] op_sel:[0,0,0] op_sel_hi:[1,0,1]
	v_pk_fma_f32 v[26:27], v[58:59], v[12:13], v[26:27] op_sel:[0,0,0] op_sel_hi:[1,0,1]
	v_pk_fma_f32 v[28:29], v[60:61], v[12:13], v[28:29] op_sel:[0,0,0] op_sel_hi:[1,0,1]
	v_pk_fma_f32 v[30:31], v[62:63], v[12:13], v[30:31] op_sel:[0,0,0] op_sel_hi:[1,0,1]
	v_pk_fma_f32 v[32:33], v[64:65], v[12:13], v[32:33] op_sel:[0,0,0] op_sel_hi:[1,0,1]
	v_pk_fma_f32 v[34:35], v[66:67], v[12:13], v[34:35] op_sel:[0,0,0] op_sel_hi:[1,0,1]
	v_pk_fma_f32 v[36:37], v[68:69], v[12:13], v[36:37] op_sel:[0,0,0] op_sel_hi:[1,0,1]
	v_pk_fma_f32 v[38:39], v[70:71], v[12:13], v[38:39] op_sel:[0,0,0] op_sel_hi:[1,0,1]
	v_pk_fma_f32 v[40:41], v[72:73], v[12:13], v[40:41] op_sel:[0,0,0] op_sel_hi:[1,0,1]
	ds_read_b128 v[46:49], v1 offset:44624
	ds_read_b128 v[50:53], v1 offset:44640
	ds_read_b128 v[54:57], v1 offset:44656
	ds_read_b128 v[58:61], v1 offset:44672
	ds_read_b128 v[62:65], v1 offset:44688
	ds_read_b128 v[66:69], v1 offset:44704
	ds_read_b128 v[70:73], v1 offset:44720
	s_waitcnt lgkmcnt(0)
	v_pk_fma_f32 v[14:15], v[78:79], v[12:13], v[14:15] op_sel:[0,1,0] op_sel_hi:[1,1,1]
	v_pk_fma_f32 v[16:17], v[80:81], v[12:13], v[16:17] op_sel:[0,1,0] op_sel_hi:[1,1,1]
	v_pk_fma_f32 v[18:19], v[82:83], v[12:13], v[18:19] op_sel:[0,1,0] op_sel_hi:[1,1,1]
	v_pk_fma_f32 v[20:21], v[84:85], v[12:13], v[20:21] op_sel:[0,1,0] op_sel_hi:[1,1,1]
	v_pk_fma_f32 v[22:23], v[86:87], v[12:13], v[22:23] op_sel:[0,1,0] op_sel_hi:[1,1,1]
	v_pk_fma_f32 v[24:25], v[88:89], v[12:13], v[24:25] op_sel:[0,1,0] op_sel_hi:[1,1,1]
	v_pk_fma_f32 v[26:27], v[226:227], v[12:13], v[26:27] op_sel:[0,1,0] op_sel_hi:[1,1,1]
	v_pk_fma_f32 v[28:29], v[228:229], v[12:13], v[28:29] op_sel:[0,1,0] op_sel_hi:[1,1,1]
	v_pk_fma_f32 v[30:31], v[230:231], v[12:13], v[30:31] op_sel:[0,1,0] op_sel_hi:[1,1,1]
	v_pk_fma_f32 v[32:33], v[232:233], v[12:13], v[32:33] op_sel:[0,1,0] op_sel_hi:[1,1,1]
	v_pk_fma_f32 v[34:35], v[234:235], v[12:13], v[34:35] op_sel:[0,1,0] op_sel_hi:[1,1,1]
	v_pk_fma_f32 v[36:37], v[236:237], v[12:13], v[36:37] op_sel:[0,1,0] op_sel_hi:[1,1,1]
	v_pk_fma_f32 v[38:39], v[238:239], v[12:13], v[38:39] op_sel:[0,1,0] op_sel_hi:[1,1,1]
	v_pk_fma_f32 v[40:41], v[240:241], v[12:13], v[40:41] op_sel:[0,1,0] op_sel_hi:[1,1,1]
	ds_read_b128 v[78:81], v1 offset:44768
	ds_read_b128 v[82:85], v1 offset:44784
	ds_read_b128 v[86:89], v1 offset:44800
	ds_read_b128 v[226:229], v1 offset:44816
	ds_read_b128 v[230:233], v1 offset:44832
	ds_read_b128 v[234:237], v1 offset:44848
	ds_read_b128 v[238:241], v1 offset:44864
	s_waitcnt lgkmcnt(0)
	v_fmac_f32_e32 v15, v47, v14
	v_pk_fma_f32 v[16:17], v[48:49], v[14:15], v[16:17] op_sel:[0,0,0] op_sel_hi:[1,0,1]
	v_pk_fma_f32 v[18:19], v[50:51], v[14:15], v[18:19] op_sel:[0,0,0] op_sel_hi:[1,0,1]
	v_pk_fma_f32 v[20:21], v[52:53], v[14:15], v[20:21] op_sel:[0,0,0] op_sel_hi:[1,0,1]
	v_pk_fma_f32 v[22:23], v[54:55], v[14:15], v[22:23] op_sel:[0,0,0] op_sel_hi:[1,0,1]
	v_pk_fma_f32 v[24:25], v[56:57], v[14:15], v[24:25] op_sel:[0,0,0] op_sel_hi:[1,0,1]
	v_pk_fma_f32 v[26:27], v[58:59], v[14:15], v[26:27] op_sel:[0,0,0] op_sel_hi:[1,0,1]
	v_pk_fma_f32 v[28:29], v[60:61], v[14:15], v[28:29] op_sel:[0,0,0] op_sel_hi:[1,0,1]
	v_pk_fma_f32 v[30:31], v[62:63], v[14:15], v[30:31] op_sel:[0,0,0] op_sel_hi:[1,0,1]
	v_pk_fma_f32 v[32:33], v[64:65], v[14:15], v[32:33] op_sel:[0,0,0] op_sel_hi:[1,0,1]
	v_pk_fma_f32 v[34:35], v[66:67], v[14:15], v[34:35] op_sel:[0,0,0] op_sel_hi:[1,0,1]
	v_pk_fma_f32 v[36:37], v[68:69], v[14:15], v[36:37] op_sel:[0,0,0] op_sel_hi:[1,0,1]
	v_pk_fma_f32 v[38:39], v[70:71], v[14:15], v[38:39] op_sel:[0,0,0] op_sel_hi:[1,0,1]
	v_pk_fma_f32 v[40:41], v[72:73], v[14:15], v[40:41] op_sel:[0,0,0] op_sel_hi:[1,0,1]
	ds_read_b128 v[46:49], v1 offset:44912
	ds_read_b128 v[50:53], v1 offset:44928
	ds_read_b128 v[54:57], v1 offset:44944
	ds_read_b128 v[58:61], v1 offset:44960
	ds_read_b128 v[62:65], v1 offset:44976
	ds_read_b128 v[66:69], v1 offset:44992
	ds_read_b128 v[70:73], v1 offset:45008
	s_waitcnt lgkmcnt(0)
	v_pk_fma_f32 v[16:17], v[80:81], v[14:15], v[16:17] op_sel:[0,1,0] op_sel_hi:[1,1,1]
	v_pk_fma_f32 v[18:19], v[82:83], v[14:15], v[18:19] op_sel:[0,1,0] op_sel_hi:[1,1,1]
	v_pk_fma_f32 v[20:21], v[84:85], v[14:15], v[20:21] op_sel:[0,1,0] op_sel_hi:[1,1,1]
	v_pk_fma_f32 v[22:23], v[86:87], v[14:15], v[22:23] op_sel:[0,1,0] op_sel_hi:[1,1,1]
	v_pk_fma_f32 v[24:25], v[88:89], v[14:15], v[24:25] op_sel:[0,1,0] op_sel_hi:[1,1,1]
	v_pk_fma_f32 v[26:27], v[226:227], v[14:15], v[26:27] op_sel:[0,1,0] op_sel_hi:[1,1,1]
	v_pk_fma_f32 v[28:29], v[228:229], v[14:15], v[28:29] op_sel:[0,1,0] op_sel_hi:[1,1,1]
	v_pk_fma_f32 v[30:31], v[230:231], v[14:15], v[30:31] op_sel:[0,1,0] op_sel_hi:[1,1,1]
	v_pk_fma_f32 v[32:33], v[232:233], v[14:15], v[32:33] op_sel:[0,1,0] op_sel_hi:[1,1,1]
	v_pk_fma_f32 v[34:35], v[234:235], v[14:15], v[34:35] op_sel:[0,1,0] op_sel_hi:[1,1,1]
	v_pk_fma_f32 v[36:37], v[236:237], v[14:15], v[36:37] op_sel:[0,1,0] op_sel_hi:[1,1,1]
	v_pk_fma_f32 v[38:39], v[238:239], v[14:15], v[38:39] op_sel:[0,1,0] op_sel_hi:[1,1,1]
	v_pk_fma_f32 v[40:41], v[240:241], v[14:15], v[40:41] op_sel:[0,1,0] op_sel_hi:[1,1,1]
	ds_read_b128 v[82:85], v1 offset:45072
	ds_read_b128 v[86:89], v1 offset:45088
	ds_read_b128 v[226:229], v1 offset:45104
	ds_read_b128 v[230:233], v1 offset:45120
	ds_read_b128 v[234:237], v1 offset:45136
	ds_read_b128 v[238:241], v1 offset:45152
	s_waitcnt lgkmcnt(0)
	v_fmac_f32_e32 v17, v49, v16
	v_pk_fma_f32 v[18:19], v[50:51], v[16:17], v[18:19] op_sel:[0,0,0] op_sel_hi:[1,0,1]
	v_pk_fma_f32 v[20:21], v[52:53], v[16:17], v[20:21] op_sel:[0,0,0] op_sel_hi:[1,0,1]
	v_pk_fma_f32 v[22:23], v[54:55], v[16:17], v[22:23] op_sel:[0,0,0] op_sel_hi:[1,0,1]
	v_pk_fma_f32 v[24:25], v[56:57], v[16:17], v[24:25] op_sel:[0,0,0] op_sel_hi:[1,0,1]
	v_pk_fma_f32 v[26:27], v[58:59], v[16:17], v[26:27] op_sel:[0,0,0] op_sel_hi:[1,0,1]
	v_pk_fma_f32 v[28:29], v[60:61], v[16:17], v[28:29] op_sel:[0,0,0] op_sel_hi:[1,0,1]
	v_pk_fma_f32 v[30:31], v[62:63], v[16:17], v[30:31] op_sel:[0,0,0] op_sel_hi:[1,0,1]
	v_pk_fma_f32 v[32:33], v[64:65], v[16:17], v[32:33] op_sel:[0,0,0] op_sel_hi:[1,0,1]
	v_pk_fma_f32 v[34:35], v[66:67], v[16:17], v[34:35] op_sel:[0,0,0] op_sel_hi:[1,0,1]
	v_pk_fma_f32 v[36:37], v[68:69], v[16:17], v[36:37] op_sel:[0,0,0] op_sel_hi:[1,0,1]
	v_pk_fma_f32 v[38:39], v[70:71], v[16:17], v[38:39] op_sel:[0,0,0] op_sel_hi:[1,0,1]
	v_pk_fma_f32 v[40:41], v[72:73], v[16:17], v[40:41] op_sel:[0,0,0] op_sel_hi:[1,0,1]
	ds_read_b128 v[50:53], v1 offset:45216
	ds_read_b128 v[54:57], v1 offset:45232
	ds_read_b128 v[58:61], v1 offset:45248
	ds_read_b128 v[62:65], v1 offset:45264
	ds_read_b128 v[66:69], v1 offset:45280
	ds_read_b128 v[70:73], v1 offset:45296
	s_waitcnt lgkmcnt(0)
	v_pk_fma_f32 v[18:19], v[82:83], v[16:17], v[18:19] op_sel:[0,1,0] op_sel_hi:[1,1,1]
	v_pk_fma_f32 v[20:21], v[84:85], v[16:17], v[20:21] op_sel:[0,1,0] op_sel_hi:[1,1,1]
	v_pk_fma_f32 v[22:23], v[86:87], v[16:17], v[22:23] op_sel:[0,1,0] op_sel_hi:[1,1,1]
	v_pk_fma_f32 v[24:25], v[88:89], v[16:17], v[24:25] op_sel:[0,1,0] op_sel_hi:[1,1,1]
	v_pk_fma_f32 v[26:27], v[226:227], v[16:17], v[26:27] op_sel:[0,1,0] op_sel_hi:[1,1,1]
	v_pk_fma_f32 v[28:29], v[228:229], v[16:17], v[28:29] op_sel:[0,1,0] op_sel_hi:[1,1,1]
	v_pk_fma_f32 v[30:31], v[230:231], v[16:17], v[30:31] op_sel:[0,1,0] op_sel_hi:[1,1,1]
	v_pk_fma_f32 v[32:33], v[232:233], v[16:17], v[32:33] op_sel:[0,1,0] op_sel_hi:[1,1,1]
	v_pk_fma_f32 v[34:35], v[234:235], v[16:17], v[34:35] op_sel:[0,1,0] op_sel_hi:[1,1,1]
	v_pk_fma_f32 v[36:37], v[236:237], v[16:17], v[36:37] op_sel:[0,1,0] op_sel_hi:[1,1,1]
	v_pk_fma_f32 v[38:39], v[238:239], v[16:17], v[38:39] op_sel:[0,1,0] op_sel_hi:[1,1,1]
	v_pk_fma_f32 v[40:41], v[240:241], v[16:17], v[40:41] op_sel:[0,1,0] op_sel_hi:[1,1,1]
	ds_read_b128 v[82:85], v1 offset:45360
	ds_read_b128 v[86:89], v1 offset:45376
	ds_read_b128 v[226:229], v1 offset:45392
	ds_read_b128 v[230:233], v1 offset:45408
	ds_read_b128 v[234:237], v1 offset:45424
	ds_read_b128 v[238:241], v1 offset:45440
	s_waitcnt lgkmcnt(0)
	v_fmac_f32_e32 v19, v51, v18
	v_pk_fma_f32 v[20:21], v[52:53], v[18:19], v[20:21] op_sel:[0,0,0] op_sel_hi:[1,0,1]
	v_pk_fma_f32 v[22:23], v[54:55], v[18:19], v[22:23] op_sel:[0,0,0] op_sel_hi:[1,0,1]
	v_pk_fma_f32 v[24:25], v[56:57], v[18:19], v[24:25] op_sel:[0,0,0] op_sel_hi:[1,0,1]
	v_pk_fma_f32 v[26:27], v[58:59], v[18:19], v[26:27] op_sel:[0,0,0] op_sel_hi:[1,0,1]
	v_pk_fma_f32 v[28:29], v[60:61], v[18:19], v[28:29] op_sel:[0,0,0] op_sel_hi:[1,0,1]
	v_pk_fma_f32 v[30:31], v[62:63], v[18:19], v[30:31] op_sel:[0,0,0] op_sel_hi:[1,0,1]
	v_pk_fma_f32 v[32:33], v[64:65], v[18:19], v[32:33] op_sel:[0,0,0] op_sel_hi:[1,0,1]
	v_pk_fma_f32 v[34:35], v[66:67], v[18:19], v[34:35] op_sel:[0,0,0] op_sel_hi:[1,0,1]
	v_pk_fma_f32 v[36:37], v[68:69], v[18:19], v[36:37] op_sel:[0,0,0] op_sel_hi:[1,0,1]
	v_pk_fma_f32 v[38:39], v[70:71], v[18:19], v[38:39] op_sel:[0,0,0] op_sel_hi:[1,0,1]
	v_pk_fma_f32 v[40:41], v[72:73], v[18:19], v[40:41] op_sel:[0,0,0] op_sel_hi:[1,0,1]
	ds_read_b128 v[50:53], v1 offset:45504
	ds_read_b128 v[54:57], v1 offset:45520
	ds_read_b128 v[58:61], v1 offset:45536
	ds_read_b128 v[62:65], v1 offset:45552
	ds_read_b128 v[66:69], v1 offset:45568
	ds_read_b128 v[70:73], v1 offset:45584
	s_waitcnt lgkmcnt(0)
	v_pk_fma_f32 v[20:21], v[84:85], v[18:19], v[20:21] op_sel:[0,1,0] op_sel_hi:[1,1,1]
	v_pk_fma_f32 v[22:23], v[86:87], v[18:19], v[22:23] op_sel:[0,1,0] op_sel_hi:[1,1,1]
	v_pk_fma_f32 v[24:25], v[88:89], v[18:19], v[24:25] op_sel:[0,1,0] op_sel_hi:[1,1,1]
	v_pk_fma_f32 v[26:27], v[226:227], v[18:19], v[26:27] op_sel:[0,1,0] op_sel_hi:[1,1,1]
	v_pk_fma_f32 v[28:29], v[228:229], v[18:19], v[28:29] op_sel:[0,1,0] op_sel_hi:[1,1,1]
	v_pk_fma_f32 v[30:31], v[230:231], v[18:19], v[30:31] op_sel:[0,1,0] op_sel_hi:[1,1,1]
	v_pk_fma_f32 v[32:33], v[232:233], v[18:19], v[32:33] op_sel:[0,1,0] op_sel_hi:[1,1,1]
	v_pk_fma_f32 v[34:35], v[234:235], v[18:19], v[34:35] op_sel:[0,1,0] op_sel_hi:[1,1,1]
	v_pk_fma_f32 v[36:37], v[236:237], v[18:19], v[36:37] op_sel:[0,1,0] op_sel_hi:[1,1,1]
	v_pk_fma_f32 v[38:39], v[238:239], v[18:19], v[38:39] op_sel:[0,1,0] op_sel_hi:[1,1,1]
	v_pk_fma_f32 v[40:41], v[240:241], v[18:19], v[40:41] op_sel:[0,1,0] op_sel_hi:[1,1,1]
	ds_read_b128 v[86:89], v1 offset:45664
	ds_read_b128 v[226:229], v1 offset:45680
	ds_read_b128 v[230:233], v1 offset:45696
	ds_read_b128 v[234:237], v1 offset:45712
	ds_read_b128 v[238:241], v1 offset:45728
	s_waitcnt lgkmcnt(0)
	v_fmac_f32_e32 v21, v53, v20
	v_pk_fma_f32 v[22:23], v[54:55], v[20:21], v[22:23] op_sel:[0,0,0] op_sel_hi:[1,0,1]
	v_pk_fma_f32 v[24:25], v[56:57], v[20:21], v[24:25] op_sel:[0,0,0] op_sel_hi:[1,0,1]
	v_pk_fma_f32 v[26:27], v[58:59], v[20:21], v[26:27] op_sel:[0,0,0] op_sel_hi:[1,0,1]
	v_pk_fma_f32 v[28:29], v[60:61], v[20:21], v[28:29] op_sel:[0,0,0] op_sel_hi:[1,0,1]
	v_pk_fma_f32 v[30:31], v[62:63], v[20:21], v[30:31] op_sel:[0,0,0] op_sel_hi:[1,0,1]
	v_pk_fma_f32 v[32:33], v[64:65], v[20:21], v[32:33] op_sel:[0,0,0] op_sel_hi:[1,0,1]
	v_pk_fma_f32 v[34:35], v[66:67], v[20:21], v[34:35] op_sel:[0,0,0] op_sel_hi:[1,0,1]
	v_pk_fma_f32 v[36:37], v[68:69], v[20:21], v[36:37] op_sel:[0,0,0] op_sel_hi:[1,0,1]
	v_pk_fma_f32 v[38:39], v[70:71], v[20:21], v[38:39] op_sel:[0,0,0] op_sel_hi:[1,0,1]
	v_pk_fma_f32 v[40:41], v[72:73], v[20:21], v[40:41] op_sel:[0,0,0] op_sel_hi:[1,0,1]
	ds_read_b128 v[54:57], v1 offset:45808
	ds_read_b128 v[58:61], v1 offset:45824
	ds_read_b128 v[62:65], v1 offset:45840
	ds_read_b128 v[66:69], v1 offset:45856
	ds_read_b128 v[70:73], v1 offset:45872
	s_waitcnt lgkmcnt(0)
	v_pk_fma_f32 v[22:23], v[86:87], v[20:21], v[22:23] op_sel:[0,1,0] op_sel_hi:[1,1,1]
	v_pk_fma_f32 v[24:25], v[88:89], v[20:21], v[24:25] op_sel:[0,1,0] op_sel_hi:[1,1,1]
	v_pk_fma_f32 v[26:27], v[226:227], v[20:21], v[26:27] op_sel:[0,1,0] op_sel_hi:[1,1,1]
	v_pk_fma_f32 v[28:29], v[228:229], v[20:21], v[28:29] op_sel:[0,1,0] op_sel_hi:[1,1,1]
	v_pk_fma_f32 v[30:31], v[230:231], v[20:21], v[30:31] op_sel:[0,1,0] op_sel_hi:[1,1,1]
	v_pk_fma_f32 v[32:33], v[232:233], v[20:21], v[32:33] op_sel:[0,1,0] op_sel_hi:[1,1,1]
	v_pk_fma_f32 v[34:35], v[234:235], v[20:21], v[34:35] op_sel:[0,1,0] op_sel_hi:[1,1,1]
	v_pk_fma_f32 v[36:37], v[236:237], v[20:21], v[36:37] op_sel:[0,1,0] op_sel_hi:[1,1,1]
	v_pk_fma_f32 v[38:39], v[238:239], v[20:21], v[38:39] op_sel:[0,1,0] op_sel_hi:[1,1,1]
	v_pk_fma_f32 v[40:41], v[240:241], v[20:21], v[40:41] op_sel:[0,1,0] op_sel_hi:[1,1,1]
	ds_read_b128 v[86:89], v1 offset:45952
	ds_read_b128 v[226:229], v1 offset:45968
	ds_read_b128 v[230:233], v1 offset:45984
	ds_read_b128 v[234:237], v1 offset:46000
	ds_read_b128 v[238:241], v1 offset:46016
	s_waitcnt lgkmcnt(0)
	v_fmac_f32_e32 v23, v55, v22
	v_pk_fma_f32 v[24:25], v[56:57], v[22:23], v[24:25] op_sel:[0,0,0] op_sel_hi:[1,0,1]
	v_pk_fma_f32 v[26:27], v[58:59], v[22:23], v[26:27] op_sel:[0,0,0] op_sel_hi:[1,0,1]
	v_pk_fma_f32 v[28:29], v[60:61], v[22:23], v[28:29] op_sel:[0,0,0] op_sel_hi:[1,0,1]
	v_pk_fma_f32 v[30:31], v[62:63], v[22:23], v[30:31] op_sel:[0,0,0] op_sel_hi:[1,0,1]
	v_pk_fma_f32 v[32:33], v[64:65], v[22:23], v[32:33] op_sel:[0,0,0] op_sel_hi:[1,0,1]
	v_pk_fma_f32 v[34:35], v[66:67], v[22:23], v[34:35] op_sel:[0,0,0] op_sel_hi:[1,0,1]
	v_pk_fma_f32 v[36:37], v[68:69], v[22:23], v[36:37] op_sel:[0,0,0] op_sel_hi:[1,0,1]
	v_pk_fma_f32 v[38:39], v[70:71], v[22:23], v[38:39] op_sel:[0,0,0] op_sel_hi:[1,0,1]
	v_pk_fma_f32 v[40:41], v[72:73], v[22:23], v[40:41] op_sel:[0,0,0] op_sel_hi:[1,0,1]
	ds_read_b128 v[54:57], v1 offset:46096
	ds_read_b128 v[58:61], v1 offset:46112
	ds_read_b128 v[62:65], v1 offset:46128
	ds_read_b128 v[66:69], v1 offset:46144
	ds_read_b128 v[70:73], v1 offset:46160
	s_waitcnt lgkmcnt(0)
	v_pk_fma_f32 v[24:25], v[88:89], v[22:23], v[24:25] op_sel:[0,1,0] op_sel_hi:[1,1,1]
	v_pk_fma_f32 v[26:27], v[226:227], v[22:23], v[26:27] op_sel:[0,1,0] op_sel_hi:[1,1,1]
	v_pk_fma_f32 v[28:29], v[228:229], v[22:23], v[28:29] op_sel:[0,1,0] op_sel_hi:[1,1,1]
	v_pk_fma_f32 v[30:31], v[230:231], v[22:23], v[30:31] op_sel:[0,1,0] op_sel_hi:[1,1,1]
	v_pk_fma_f32 v[32:33], v[232:233], v[22:23], v[32:33] op_sel:[0,1,0] op_sel_hi:[1,1,1]
	v_pk_fma_f32 v[34:35], v[234:235], v[22:23], v[34:35] op_sel:[0,1,0] op_sel_hi:[1,1,1]
	v_pk_fma_f32 v[36:37], v[236:237], v[22:23], v[36:37] op_sel:[0,1,0] op_sel_hi:[1,1,1]
	v_pk_fma_f32 v[38:39], v[238:239], v[22:23], v[38:39] op_sel:[0,1,0] op_sel_hi:[1,1,1]
	v_pk_fma_f32 v[40:41], v[240:241], v[22:23], v[40:41] op_sel:[0,1,0] op_sel_hi:[1,1,1]
	ds_read_b128 v[226:229], v1 offset:46256
	ds_read_b128 v[230:233], v1 offset:46272
	ds_read_b128 v[234:237], v1 offset:46288
	ds_read_b128 v[238:241], v1 offset:46304
	s_waitcnt lgkmcnt(0)
	v_fmac_f32_e32 v25, v57, v24
	v_pk_fma_f32 v[26:27], v[58:59], v[24:25], v[26:27] op_sel:[0,0,0] op_sel_hi:[1,0,1]
	v_pk_fma_f32 v[28:29], v[60:61], v[24:25], v[28:29] op_sel:[0,0,0] op_sel_hi:[1,0,1]
	v_pk_fma_f32 v[30:31], v[62:63], v[24:25], v[30:31] op_sel:[0,0,0] op_sel_hi:[1,0,1]
	v_pk_fma_f32 v[32:33], v[64:65], v[24:25], v[32:33] op_sel:[0,0,0] op_sel_hi:[1,0,1]
	v_pk_fma_f32 v[34:35], v[66:67], v[24:25], v[34:35] op_sel:[0,0,0] op_sel_hi:[1,0,1]
	v_pk_fma_f32 v[36:37], v[68:69], v[24:25], v[36:37] op_sel:[0,0,0] op_sel_hi:[1,0,1]
	v_pk_fma_f32 v[38:39], v[70:71], v[24:25], v[38:39] op_sel:[0,0,0] op_sel_hi:[1,0,1]
	v_pk_fma_f32 v[40:41], v[72:73], v[24:25], v[40:41] op_sel:[0,0,0] op_sel_hi:[1,0,1]
	ds_read_b128 v[58:61], v1 offset:46400
	ds_read_b128 v[62:65], v1 offset:46416
	ds_read_b128 v[66:69], v1 offset:46432
	ds_read_b128 v[70:73], v1 offset:46448
	s_waitcnt lgkmcnt(0)
	v_pk_fma_f32 v[26:27], v[226:227], v[24:25], v[26:27] op_sel:[0,1,0] op_sel_hi:[1,1,1]
	v_pk_fma_f32 v[28:29], v[228:229], v[24:25], v[28:29] op_sel:[0,1,0] op_sel_hi:[1,1,1]
	v_pk_fma_f32 v[30:31], v[230:231], v[24:25], v[30:31] op_sel:[0,1,0] op_sel_hi:[1,1,1]
	v_pk_fma_f32 v[32:33], v[232:233], v[24:25], v[32:33] op_sel:[0,1,0] op_sel_hi:[1,1,1]
	v_pk_fma_f32 v[34:35], v[234:235], v[24:25], v[34:35] op_sel:[0,1,0] op_sel_hi:[1,1,1]
	v_pk_fma_f32 v[36:37], v[236:237], v[24:25], v[36:37] op_sel:[0,1,0] op_sel_hi:[1,1,1]
	v_pk_fma_f32 v[38:39], v[238:239], v[24:25], v[38:39] op_sel:[0,1,0] op_sel_hi:[1,1,1]
	v_pk_fma_f32 v[40:41], v[240:241], v[24:25], v[40:41] op_sel:[0,1,0] op_sel_hi:[1,1,1]
	ds_read_b128 v[226:229], v1 offset:46544
	ds_read_b128 v[230:233], v1 offset:46560
	ds_read_b128 v[234:237], v1 offset:46576
	ds_read_b128 v[238:241], v1 offset:46592
	s_waitcnt lgkmcnt(0)
	v_fmac_f32_e32 v27, v59, v26
	v_pk_fma_f32 v[28:29], v[60:61], v[26:27], v[28:29] op_sel:[0,0,0] op_sel_hi:[1,0,1]
	v_pk_fma_f32 v[30:31], v[62:63], v[26:27], v[30:31] op_sel:[0,0,0] op_sel_hi:[1,0,1]
	v_pk_fma_f32 v[32:33], v[64:65], v[26:27], v[32:33] op_sel:[0,0,0] op_sel_hi:[1,0,1]
	v_pk_fma_f32 v[34:35], v[66:67], v[26:27], v[34:35] op_sel:[0,0,0] op_sel_hi:[1,0,1]
	v_pk_fma_f32 v[36:37], v[68:69], v[26:27], v[36:37] op_sel:[0,0,0] op_sel_hi:[1,0,1]
	v_pk_fma_f32 v[38:39], v[70:71], v[26:27], v[38:39] op_sel:[0,0,0] op_sel_hi:[1,0,1]
	v_pk_fma_f32 v[40:41], v[72:73], v[26:27], v[40:41] op_sel:[0,0,0] op_sel_hi:[1,0,1]
	ds_read_b128 v[58:61], v1 offset:46688
	ds_read_b128 v[62:65], v1 offset:46704
	ds_read_b128 v[66:69], v1 offset:46720
	ds_read_b128 v[70:73], v1 offset:46736
	s_waitcnt lgkmcnt(0)
	v_pk_fma_f32 v[28:29], v[228:229], v[26:27], v[28:29] op_sel:[0,1,0] op_sel_hi:[1,1,1]
	v_pk_fma_f32 v[30:31], v[230:231], v[26:27], v[30:31] op_sel:[0,1,0] op_sel_hi:[1,1,1]
	v_pk_fma_f32 v[32:33], v[232:233], v[26:27], v[32:33] op_sel:[0,1,0] op_sel_hi:[1,1,1]
	v_pk_fma_f32 v[34:35], v[234:235], v[26:27], v[34:35] op_sel:[0,1,0] op_sel_hi:[1,1,1]
	v_pk_fma_f32 v[36:37], v[236:237], v[26:27], v[36:37] op_sel:[0,1,0] op_sel_hi:[1,1,1]
	v_pk_fma_f32 v[38:39], v[238:239], v[26:27], v[38:39] op_sel:[0,1,0] op_sel_hi:[1,1,1]
	v_pk_fma_f32 v[40:41], v[240:241], v[26:27], v[40:41] op_sel:[0,1,0] op_sel_hi:[1,1,1]
	ds_read_b128 v[230:233], v1 offset:46848
	ds_read_b128 v[234:237], v1 offset:46864
	ds_read_b128 v[238:241], v1 offset:46880
	s_waitcnt lgkmcnt(0)
	v_fmac_f32_e32 v29, v61, v28
	v_pk_fma_f32 v[30:31], v[62:63], v[28:29], v[30:31] op_sel:[0,0,0] op_sel_hi:[1,0,1]
	v_pk_fma_f32 v[32:33], v[64:65], v[28:29], v[32:33] op_sel:[0,0,0] op_sel_hi:[1,0,1]
	v_pk_fma_f32 v[34:35], v[66:67], v[28:29], v[34:35] op_sel:[0,0,0] op_sel_hi:[1,0,1]
	v_pk_fma_f32 v[36:37], v[68:69], v[28:29], v[36:37] op_sel:[0,0,0] op_sel_hi:[1,0,1]
	v_pk_fma_f32 v[38:39], v[70:71], v[28:29], v[38:39] op_sel:[0,0,0] op_sel_hi:[1,0,1]
	v_pk_fma_f32 v[40:41], v[72:73], v[28:29], v[40:41] op_sel:[0,0,0] op_sel_hi:[1,0,1]
	ds_read_b128 v[62:65], v1 offset:46992
	ds_read_b128 v[66:69], v1 offset:47008
	ds_read_b128 v[70:73], v1 offset:47024
	s_waitcnt lgkmcnt(0)
	v_pk_fma_f32 v[30:31], v[230:231], v[28:29], v[30:31] op_sel:[0,1,0] op_sel_hi:[1,1,1]
	v_pk_fma_f32 v[32:33], v[232:233], v[28:29], v[32:33] op_sel:[0,1,0] op_sel_hi:[1,1,1]
	v_pk_fma_f32 v[34:35], v[234:235], v[28:29], v[34:35] op_sel:[0,1,0] op_sel_hi:[1,1,1]
	v_pk_fma_f32 v[36:37], v[236:237], v[28:29], v[36:37] op_sel:[0,1,0] op_sel_hi:[1,1,1]
	v_pk_fma_f32 v[38:39], v[238:239], v[28:29], v[38:39] op_sel:[0,1,0] op_sel_hi:[1,1,1]
	v_pk_fma_f32 v[40:41], v[240:241], v[28:29], v[40:41] op_sel:[0,1,0] op_sel_hi:[1,1,1]
	ds_read_b128 v[230:233], v1 offset:47136
	ds_read_b128 v[234:237], v1 offset:47152
	ds_read_b128 v[238:241], v1 offset:47168
	s_waitcnt lgkmcnt(0)
	v_fmac_f32_e32 v31, v63, v30
	v_pk_fma_f32 v[32:33], v[64:65], v[30:31], v[32:33] op_sel:[0,0,0] op_sel_hi:[1,0,1]
	v_pk_fma_f32 v[34:35], v[66:67], v[30:31], v[34:35] op_sel:[0,0,0] op_sel_hi:[1,0,1]
	v_pk_fma_f32 v[36:37], v[68:69], v[30:31], v[36:37] op_sel:[0,0,0] op_sel_hi:[1,0,1]
	v_pk_fma_f32 v[38:39], v[70:71], v[30:31], v[38:39] op_sel:[0,0,0] op_sel_hi:[1,0,1]
	v_pk_fma_f32 v[40:41], v[72:73], v[30:31], v[40:41] op_sel:[0,0,0] op_sel_hi:[1,0,1]
	ds_read_b128 v[62:65], v1 offset:47280
	ds_read_b128 v[66:69], v1 offset:47296
	ds_read_b128 v[70:73], v1 offset:47312
	s_waitcnt lgkmcnt(0)
	v_pk_fma_f32 v[32:33], v[232:233], v[30:31], v[32:33] op_sel:[0,1,0] op_sel_hi:[1,1,1]
	v_pk_fma_f32 v[34:35], v[234:235], v[30:31], v[34:35] op_sel:[0,1,0] op_sel_hi:[1,1,1]
	v_pk_fma_f32 v[36:37], v[236:237], v[30:31], v[36:37] op_sel:[0,1,0] op_sel_hi:[1,1,1]
	v_pk_fma_f32 v[38:39], v[238:239], v[30:31], v[38:39] op_sel:[0,1,0] op_sel_hi:[1,1,1]
	v_pk_fma_f32 v[40:41], v[240:241], v[30:31], v[40:41] op_sel:[0,1,0] op_sel_hi:[1,1,1]
	ds_read_b128 v[234:237], v1 offset:47440
	ds_read_b128 v[238:241], v1 offset:47456
	s_waitcnt lgkmcnt(0)
	v_fmac_f32_e32 v33, v65, v32
	v_pk_fma_f32 v[34:35], v[66:67], v[32:33], v[34:35] op_sel:[0,0,0] op_sel_hi:[1,0,1]
	v_pk_fma_f32 v[36:37], v[68:69], v[32:33], v[36:37] op_sel:[0,0,0] op_sel_hi:[1,0,1]
	v_pk_fma_f32 v[38:39], v[70:71], v[32:33], v[38:39] op_sel:[0,0,0] op_sel_hi:[1,0,1]
	v_pk_fma_f32 v[40:41], v[72:73], v[32:33], v[40:41] op_sel:[0,0,0] op_sel_hi:[1,0,1]
	ds_read_b128 v[66:69], v1 offset:47584
	ds_read_b128 v[70:73], v1 offset:47600
	s_waitcnt lgkmcnt(0)
	v_pk_fma_f32 v[34:35], v[234:235], v[32:33], v[34:35] op_sel:[0,1,0] op_sel_hi:[1,1,1]
	v_pk_fma_f32 v[36:37], v[236:237], v[32:33], v[36:37] op_sel:[0,1,0] op_sel_hi:[1,1,1]
	v_pk_fma_f32 v[38:39], v[238:239], v[32:33], v[38:39] op_sel:[0,1,0] op_sel_hi:[1,1,1]
	v_pk_fma_f32 v[40:41], v[240:241], v[32:33], v[40:41] op_sel:[0,1,0] op_sel_hi:[1,1,1]
	ds_read_b128 v[234:237], v1 offset:47728
	ds_read_b128 v[238:241], v1 offset:47744
	s_waitcnt lgkmcnt(0)
	v_fmac_f32_e32 v35, v67, v34
	v_pk_fma_f32 v[36:37], v[68:69], v[34:35], v[36:37] op_sel:[0,0,0] op_sel_hi:[1,0,1]
	v_pk_fma_f32 v[38:39], v[70:71], v[34:35], v[38:39] op_sel:[0,0,0] op_sel_hi:[1,0,1]
	v_pk_fma_f32 v[40:41], v[72:73], v[34:35], v[40:41] op_sel:[0,0,0] op_sel_hi:[1,0,1]
	ds_read_b128 v[66:69], v1 offset:47872
	ds_read_b128 v[70:73], v1 offset:47888
	s_waitcnt lgkmcnt(0)
	v_pk_fma_f32 v[36:37], v[236:237], v[34:35], v[36:37] op_sel:[0,1,0] op_sel_hi:[1,1,1]
	v_pk_fma_f32 v[38:39], v[238:239], v[34:35], v[38:39] op_sel:[0,1,0] op_sel_hi:[1,1,1]
	v_pk_fma_f32 v[40:41], v[240:241], v[34:35], v[40:41] op_sel:[0,1,0] op_sel_hi:[1,1,1]
	ds_read_b128 v[238:241], v1 offset:48032
	s_waitcnt lgkmcnt(0)
	v_fmac_f32_e32 v37, v69, v36
	v_pk_fma_f32 v[38:39], v[70:71], v[36:37], v[38:39] op_sel:[0,0,0] op_sel_hi:[1,0,1]
	v_pk_fma_f32 v[40:41], v[72:73], v[36:37], v[40:41] op_sel:[0,0,0] op_sel_hi:[1,0,1]
	ds_read_b128 v[70:73], v1 offset:48176
	s_waitcnt lgkmcnt(0)
	v_pk_fma_f32 v[38:39], v[238:239], v[36:37], v[38:39] op_sel:[0,1,0] op_sel_hi:[1,1,1]
	v_pk_fma_f32 v[40:41], v[240:241], v[36:37], v[40:41] op_sel:[0,1,0] op_sel_hi:[1,1,1]
	ds_read_b128 v[238:241], v1 offset:48320
	s_waitcnt lgkmcnt(0)
	v_fmac_f32_e32 v39, v71, v38
	v_pk_fma_f32 v[40:41], v[72:73], v[38:39], v[40:41] op_sel:[0,0,0] op_sel_hi:[1,0,1]
	ds_read_b128 v[70:73], v1 offset:48464
	s_waitcnt lgkmcnt(0)
	v_pk_fma_f32 v[40:41], v[240:241], v[38:39], v[40:41] op_sel:[0,1,0] op_sel_hi:[1,1,1]
	s_waitcnt lgkmcnt(0)
	v_fmac_f32_e32 v41, v73, v40
	ds_write_b32 v135, v10 offset:57856
	ds_write_b32 v135, v11 offset:58000
	ds_write_b32 v135, v12 offset:58144
	ds_write_b32 v135, v13 offset:58288
	ds_write_b32 v135, v14 offset:58432
	ds_write_b32 v135, v15 offset:58576
	ds_write_b32 v135, v16 offset:58720
	ds_write_b32 v135, v17 offset:58864
	ds_write_b32 v135, v18 offset:59008
	ds_write_b32 v135, v19 offset:59152
	ds_write_b32 v135, v20 offset:59296
	ds_write_b32 v135, v21 offset:59440
	ds_write_b32 v135, v22 offset:59584
	ds_write_b32 v135, v23 offset:59728
	ds_write_b32 v135, v24 offset:59872
	ds_write_b32 v135, v25 offset:60016
	ds_write_b32 v135, v26 offset:60160
	ds_write_b32 v135, v27 offset:60304
	ds_write_b32 v135, v28 offset:60448
	ds_write_b32 v135, v29 offset:60592
	ds_write_b32 v135, v30 offset:60736
	ds_write_b32 v135, v31 offset:60880
	ds_write_b32 v135, v32 offset:61024
	ds_write_b32 v135, v33 offset:61168
	ds_write_b32 v135, v34 offset:61312
	ds_write_b32 v135, v35 offset:61456
	ds_write_b32 v135, v36 offset:61600
	ds_write_b32 v135, v37 offset:61744
	ds_write_b32 v135, v38 offset:61888
	ds_write_b32 v135, v39 offset:62032
	ds_write_b32 v135, v40 offset:62176
	ds_write_b32 v135, v41 offset:62320
	s_branch .Ldc_b3
; __device__ __forceinline__ void dn_task(const Params& p, int l, int task, char* smem) {
;     ...
;     {
;       const int did = tid >> 2, pp = did >> 2, wh = did & 3, part = tid & 3;
;       const float* xr = (wh == 0) ? (ks + (2 * pp + 1) * 68) : (wh == 1) ? (qs + (2 * pp) * 68) : (qs + (2 * pp + 1) * 68);
;       const float* yr = (wh == 3) ? (ks + (2 * pp + 1) * 68) : (ks + (2 * pp) * 68);
;       float sdot = 0.f;
; #pragma unroll
;       for (int i = 0; i < 16; ++i) sdot += xr[part * 16 + i] * yr[part * 16 + i];
;       sdot = quad_sum(sdot);
;       if (part == 0) dots[did] = sdot;
;     }
.Ldc_s2k:
	ds_read_b128 v[10:13], v224 offset:0
	ds_read_b128 v[14:17], v224 offset:16
	ds_read_b128 v[18:21], v224 offset:32
	ds_read_b128 v[22:25], v224 offset:48
	ds_read_b128 v[42:45], v224 offset:8704
	ds_read_b128 v[46:49], v224 offset:8720
	ds_read_b128 v[50:53], v224 offset:8736
	ds_read_b128 v[54:57], v224 offset:8752
	ds_read_b32 v82, v225 offset:53248
	ds_read_b32 v83, v225 offset:53392
	ds_read_b32 v84, v225 offset:53536
	ds_read_b32 v85, v225 offset:53680
	ds_read_b128 v[26:29], v224 offset:4352
	ds_read_b128 v[30:33], v224 offset:4368
	ds_read_b128 v[34:37], v224 offset:4384
	ds_read_b128 v[38:41], v224 offset:4400
	ds_read_b128 v[66:69], v224 offset:8704
	ds_read_b128 v[70:73], v224 offset:8720
	ds_read_b128 v[74:77], v224 offset:8736
	ds_read_b128 v[78:81], v224 offset:8752
	ds_read_b32 v86, v225 offset:55552
	ds_read_b32 v87, v225 offset:55696
	ds_read_b32 v88, v225 offset:55840
	ds_read_b32 v89, v225 offset:55984
	s_waitcnt lgkmcnt(0)
	v_mfma_f32_16x16x4_f32 v[58:61], v10, v42, 0
	v_mfma_f32_16x16x4_f32 v[58:61], v11, v43, v[58:61]
	v_mfma_f32_16x16x4_f32 v[58:61], v12, v44, v[58:61]
	v_mfma_f32_16x16x4_f32 v[58:61], v13, v45, v[58:61]
	v_mfma_f32_16x16x4_f32 v[58:61], v14, v46, v[58:61]
	v_mfma_f32_16x16x4_f32 v[58:61], v15, v47, v[58:61]
	v_mfma_f32_16x16x4_f32 v[58:61], v16, v48, v[58:61]
	v_mfma_f32_16x16x4_f32 v[58:61], v17, v49, v[58:61]
	v_mfma_f32_16x16x4_f32 v[58:61], v18, v50, v[58:61]
	v_mfma_f32_16x16x4_f32 v[58:61], v19, v51, v[58:61]
	v_mfma_f32_16x16x4_f32 v[58:61], v20, v52, v[58:61]
	v_mfma_f32_16x16x4_f32 v[58:61], v21, v53, v[58:61]
	v_mfma_f32_16x16x4_f32 v[58:61], v22, v54, v[58:61]
	v_mfma_f32_16x16x4_f32 v[58:61], v23, v55, v[58:61]
	v_mfma_f32_16x16x4_f32 v[58:61], v24, v56, v[58:61]
	v_mfma_f32_16x16x4_f32 v[58:61], v25, v57, v[58:61]
	ds_read_b128 v[10:13], v224 offset:4352
	ds_read_b128 v[14:17], v224 offset:4368
	ds_read_b128 v[18:21], v224 offset:4384
	ds_read_b128 v[22:25], v224 offset:4400
	ds_read_b128 v[42:45], v224 offset:13056
	ds_read_b128 v[46:49], v224 offset:13072
	ds_read_b128 v[50:53], v224 offset:13088
	ds_read_b128 v[54:57], v224 offset:13104
	ds_read_b32 v226, v225 offset:55616
	ds_read_b32 v227, v225 offset:55760
	ds_read_b32 v228, v225 offset:55904
	ds_read_b32 v229, v225 offset:56048
	s_waitcnt lgkmcnt(0)
	v_mfma_f32_16x16x4_f32 v[62:65], v26, v66, 0
	v_mfma_f32_16x16x4_f32 v[62:65], v27, v67, v[62:65]
	v_mfma_f32_16x16x4_f32 v[62:65], v28, v68, v[62:65]
	v_mfma_f32_16x16x4_f32 v[62:65], v29, v69, v[62:65]
	v_mfma_f32_16x16x4_f32 v[62:65], v30, v70, v[62:65]
	v_mfma_f32_16x16x4_f32 v[62:65], v31, v71, v[62:65]
	v_mfma_f32_16x16x4_f32 v[62:65], v32, v72, v[62:65]
	v_mfma_f32_16x16x4_f32 v[62:65], v33, v73, v[62:65]
	v_mfma_f32_16x16x4_f32 v[62:65], v34, v74, v[62:65]
	v_mfma_f32_16x16x4_f32 v[62:65], v35, v75, v[62:65]
	v_mfma_f32_16x16x4_f32 v[62:65], v36, v76, v[62:65]
	v_mfma_f32_16x16x4_f32 v[62:65], v37, v77, v[62:65]
	v_mfma_f32_16x16x4_f32 v[62:65], v38, v78, v[62:65]
	v_mfma_f32_16x16x4_f32 v[62:65], v39, v79, v[62:65]
	v_mfma_f32_16x16x4_f32 v[62:65], v40, v80, v[62:65]
	v_mfma_f32_16x16x4_f32 v[62:65], v41, v81, v[62:65]
	v_mul_f32_e32 v58, v58, v82
	ds_write_b32 v225, v58 offset:48640
	v_mul_f32_e32 v59, v59, v83
	ds_write_b32 v225, v59 offset:48784
	v_mul_f32_e32 v60, v60, v84
	ds_write_b32 v225, v60 offset:48928
	v_mul_f32_e32 v61, v61, v85
	ds_write_b32 v225, v61 offset:49072
	s_waitcnt lgkmcnt(0)
	v_mfma_f32_16x16x4_f32 v[58:61], v10, v42, 0
	v_mfma_f32_16x16x4_f32 v[58:61], v11, v43, v[58:61]
	v_mfma_f32_16x16x4_f32 v[58:61], v12, v44, v[58:61]
	v_mfma_f32_16x16x4_f32 v[58:61], v13, v45, v[58:61]
	v_mfma_f32_16x16x4_f32 v[58:61], v14, v46, v[58:61]
	v_mfma_f32_16x16x4_f32 v[58:61], v15, v47, v[58:61]
	v_mfma_f32_16x16x4_f32 v[58:61], v16, v48, v[58:61]
	v_mfma_f32_16x16x4_f32 v[58:61], v17, v49, v[58:61]
	v_mfma_f32_16x16x4_f32 v[58:61], v18, v50, v[58:61]
	v_mfma_f32_16x16x4_f32 v[58:61], v19, v51, v[58:61]
	v_mfma_f32_16x16x4_f32 v[58:61], v20, v52, v[58:61]
	v_mfma_f32_16x16x4_f32 v[58:61], v21, v53, v[58:61]
	v_mfma_f32_16x16x4_f32 v[58:61], v22, v54, v[58:61]
	v_mfma_f32_16x16x4_f32 v[58:61], v23, v55, v[58:61]
	v_mfma_f32_16x16x4_f32 v[58:61], v24, v56, v[58:61]
	v_mfma_f32_16x16x4_f32 v[58:61], v25, v57, v[58:61]
	v_mul_f32_e32 v62, v62, v86
	ds_write_b32 v225, v62 offset:50944
	v_mul_f32_e32 v63, v63, v87
	ds_write_b32 v225, v63 offset:51088
	v_mul_f32_e32 v64, v64, v88
	ds_write_b32 v225, v64 offset:51232
	v_mul_f32_e32 v65, v65, v89
	ds_write_b32 v225, v65 offset:51376
	s_nop 7
	s_nop 3
	v_mul_f32_e32 v58, v58, v226
	ds_write_b32 v225, v58 offset:51008
	v_mul_f32_e32 v59, v59, v227
	ds_write_b32 v225, v59 offset:51152
	v_mul_f32_e32 v60, v60, v228
	ds_write_b32 v225, v60 offset:51296
	v_mul_f32_e32 v61, v61, v229
	ds_write_b32 v225, v61 offset:51440
	s_branch .Ldc_b3
